# v36 + nt on the P2 residual epilogue's x_in loads (last read of the input x)
# speedup vs baseline: 1.0031x; 1.0031x over previous
.LBB0_928:
	s_or_b64 exec, exec, s[8:9]
	v_lshl_or_b32 v160, s14, 8, v173
	v_ashrrev_i32_e32 v161, 31, v160
	v_cmp_ne_u64_e32 vcc, 0, v[132:133]
	v_mov_b32_e32 v130, 0
	v_lshl_add_u64 v[166:167], v[160:161], 2, v[132:133]
	v_mov_b32_e32 v136, 0
	v_mov_b32_e32 v137, 0
	v_mov_b32_e32 v138, 0
	v_mov_b32_e32 v139, 0
	v_mov_b32_e32 v132, 0
	v_mov_b32_e32 v133, 0
	v_mov_b32_e32 v134, 0
	v_mov_b32_e32 v135, 0
	s_and_saveexec_b64 s[8:9], vcc
	s_cbranch_execz .LBB0_930
	global_load_dwordx4 v[136:139], v[166:167], off nt
	global_load_dwordx4 v[132:135], v[166:167], off offset:16 nt
.LBB0_930:
	s_or_b64 exec, exec, s[8:9]
	v_add_u32_e32 v131, 0xffffbc00, v162
	v_cmp_gt_i32_e64 s[8:9], s87, v162
	v_mov_b32_e32 v148, s27
	v_lshlrev_b64 v[164:165], 11, v[162:163]
	v_cndmask_b32_e64 v178, v131, v162, s[8:9]
	v_mov_b32_e32 v131, s63
	v_cndmask_b32_e64 v179, 0, v163, s[8:9]
	v_cndmask_b32_e64 v181, v131, v148, s[8:9]
	v_mov_b32_e32 v131, s62
	v_mov_b32_e32 v148, s26
	v_cndmask_b32_e64 v180, v131, v148, s[8:9]
	v_lshlrev_b64 v[178:179], 12, v[178:179]
	v_lshl_add_u64 v[178:179], v[180:181], 0, v[178:179]
	s_waitcnt vmcnt(0)
	v_pk_fma_f32 v[128:129], v[128:129], 0.5, v[138:139] op_sel_hi:[1,0,1]
	v_pk_fma_f32 v[126:127], v[126:127], 0.5, v[136:137] op_sel_hi:[1,0,1]
	v_pk_fma_f32 v[124:125], v[124:125], 0.5, v[134:135] op_sel_hi:[1,0,1]
	v_pk_fma_f32 v[122:123], v[122:123], 0.5, v[132:133] op_sel_hi:[1,0,1]
	v_lshl_add_u64 v[136:137], s[88:89], 0, v[164:165]
	v_lshl_add_u64 v[138:139], v[160:161], 2, v[178:179]
	v_cvt_pk_bf16_f32 v132, v126, v127
	v_cvt_pk_bf16_f32 v133, v128, v129
	v_cvt_pk_bf16_f32 v134, v122, v123
	v_cvt_pk_bf16_f32 v135, v124, v125
	v_lshl_add_u64 v[164:165], v[160:161], 1, v[136:137]
	global_store_dwordx4 v[138:139], v[126:129], off
	global_store_dwordx4 v[138:139], v[122:125], off offset:16
	global_store_dwordx4 v[164:165], v[132:135], off
	v_mov_b32_e32 v131, 0
	v_mov_b32_e32 v136, 0
	v_mov_b32_e32 v132, 0
	v_mov_b32_e32 v133, 0
	v_mov_b32_e32 v134, 0
	v_mov_b32_e32 v135, 0
	v_mov_b32_e32 v137, 0
	s_and_saveexec_b64 s[8:9], vcc
	s_cbranch_execz .LBB0_932
	global_load_dwordx4 v[130:133], v[166:167], off offset:512 nt
	global_load_dwordx4 v[134:137], v[166:167], off offset:528 nt

.LBB0_941:
	s_or_b64 exec, exec, s[8:9]
	v_cmp_ne_u64_e32 vcc, 0, v[116:117]
	v_mov_b32_e32 v114, 0
	v_lshl_add_u64 v[128:129], v[160:161], 2, v[116:117]
	v_mov_b32_e32 v120, 0
	v_mov_b32_e32 v121, 0
	v_mov_b32_e32 v122, 0
	v_mov_b32_e32 v123, 0
	v_mov_b32_e32 v116, 0
	v_mov_b32_e32 v117, 0
	v_mov_b32_e32 v118, 0
	v_mov_b32_e32 v119, 0
	s_and_saveexec_b64 s[8:9], vcc
	s_cbranch_execz .LBB0_943
	global_load_dwordx4 v[120:123], v[128:129], off nt
	global_load_dwordx4 v[116:119], v[128:129], off offset:16 nt
.LBB0_943:
	s_or_b64 exec, exec, s[8:9]
	s_waitcnt lgkmcnt(0)
	v_add_u32_e32 v115, 0xffffbc10, v162
	v_cmp_gt_i32_e64 s[8:9], s87, v124
	v_mov_b32_e32 v132, s27
	v_lshlrev_b64 v[126:127], 11, v[124:125]
	v_cndmask_b32_e64 v130, v115, v124, s[8:9]
	v_mov_b32_e32 v115, s63
	v_cndmask_b32_e64 v131, 0, v125, s[8:9]
	v_cndmask_b32_e64 v133, v115, v132, s[8:9]
	v_mov_b32_e32 v115, s62
	v_mov_b32_e32 v132, s26
	v_cndmask_b32_e64 v132, v115, v132, s[8:9]
	v_lshlrev_b64 v[130:131], 12, v[130:131]
	v_lshl_add_u64 v[130:131], v[132:133], 0, v[130:131]
	s_waitcnt vmcnt(1)
	v_pk_fma_f32 v[112:113], v[112:113], 0.5, v[122:123] op_sel_hi:[1,0,1]
	v_pk_fma_f32 v[110:111], v[110:111], 0.5, v[120:121] op_sel_hi:[1,0,1]
	s_waitcnt vmcnt(0)
	v_pk_fma_f32 v[108:109], v[108:109], 0.5, v[118:119] op_sel_hi:[1,0,1]
	v_pk_fma_f32 v[106:107], v[106:107], 0.5, v[116:117] op_sel_hi:[1,0,1]
	v_lshl_add_u64 v[120:121], s[88:89], 0, v[126:127]
	v_lshl_add_u64 v[122:123], v[160:161], 2, v[130:131]
	v_cvt_pk_bf16_f32 v116, v110, v111
	v_cvt_pk_bf16_f32 v117, v112, v113
	v_cvt_pk_bf16_f32 v118, v106, v107
	v_cvt_pk_bf16_f32 v119, v108, v109
	v_lshl_add_u64 v[126:127], v[160:161], 1, v[120:121]
	global_store_dwordx4 v[122:123], v[110:113], off
	global_store_dwordx4 v[122:123], v[106:109], off offset:16
	global_store_dwordx4 v[126:127], v[116:119], off
	v_mov_b32_e32 v115, 0
	v_mov_b32_e32 v120, 0
	v_mov_b32_e32 v116, 0
	v_mov_b32_e32 v117, 0
	v_mov_b32_e32 v118, 0
	v_mov_b32_e32 v119, 0
	v_mov_b32_e32 v121, 0
	s_and_saveexec_b64 s[8:9], vcc
	s_cbranch_execz .LBB0_945
	global_load_dwordx4 v[114:117], v[128:129], off offset:512 nt
	global_load_dwordx4 v[118:121], v[128:129], off offset:528 nt

.LBB0_954:
	s_or_b64 exec, exec, s[8:9]
	v_cmp_ne_u64_e32 vcc, 0, v[100:101]
	v_mov_b32_e32 v98, 0
	v_lshl_add_u64 v[112:113], v[160:161], 2, v[100:101]
	v_mov_b32_e32 v104, 0
	v_mov_b32_e32 v105, 0
	v_mov_b32_e32 v106, 0
	v_mov_b32_e32 v107, 0
	v_mov_b32_e32 v100, 0
	v_mov_b32_e32 v101, 0
	v_mov_b32_e32 v102, 0
	v_mov_b32_e32 v103, 0
	s_and_saveexec_b64 s[8:9], vcc
	s_cbranch_execz .LBB0_956
	global_load_dwordx4 v[104:107], v[112:113], off nt
	global_load_dwordx4 v[100:103], v[112:113], off offset:16 nt
.LBB0_956:
	s_or_b64 exec, exec, s[8:9]
	s_waitcnt lgkmcnt(0)
	v_add_u32_e32 v99, 0xffffbc20, v162
	v_cmp_gt_i32_e64 s[8:9], s87, v108
	v_mov_b32_e32 v116, s27
	v_lshlrev_b64 v[110:111], 11, v[108:109]
	v_cndmask_b32_e64 v114, v99, v108, s[8:9]
	v_mov_b32_e32 v99, s63
	v_cndmask_b32_e64 v115, 0, v109, s[8:9]
	v_cndmask_b32_e64 v117, v99, v116, s[8:9]
	v_mov_b32_e32 v99, s62
	v_mov_b32_e32 v116, s26
	v_cndmask_b32_e64 v116, v99, v116, s[8:9]
	v_lshlrev_b64 v[114:115], 12, v[114:115]
	v_lshl_add_u64 v[114:115], v[116:117], 0, v[114:115]
	s_waitcnt vmcnt(1)
	v_pk_fma_f32 v[96:97], v[96:97], 0.5, v[106:107] op_sel_hi:[1,0,1]
	v_pk_fma_f32 v[94:95], v[94:95], 0.5, v[104:105] op_sel_hi:[1,0,1]
	s_waitcnt vmcnt(0)
	v_pk_fma_f32 v[92:93], v[92:93], 0.5, v[102:103] op_sel_hi:[1,0,1]
	v_pk_fma_f32 v[90:91], v[90:91], 0.5, v[100:101] op_sel_hi:[1,0,1]
	v_lshl_add_u64 v[104:105], s[88:89], 0, v[110:111]
	v_lshl_add_u64 v[106:107], v[160:161], 2, v[114:115]
	v_cvt_pk_bf16_f32 v100, v94, v95
	v_cvt_pk_bf16_f32 v101, v96, v97
	v_cvt_pk_bf16_f32 v102, v90, v91
	v_cvt_pk_bf16_f32 v103, v92, v93
	v_lshl_add_u64 v[110:111], v[160:161], 1, v[104:105]
	global_store_dwordx4 v[106:107], v[94:97], off
	global_store_dwordx4 v[106:107], v[90:93], off offset:16
	global_store_dwordx4 v[110:111], v[100:103], off
	v_mov_b32_e32 v99, 0
	v_mov_b32_e32 v104, 0
	v_mov_b32_e32 v100, 0
	v_mov_b32_e32 v101, 0
	v_mov_b32_e32 v102, 0
	v_mov_b32_e32 v103, 0
	v_mov_b32_e32 v105, 0
	s_and_saveexec_b64 s[8:9], vcc
	s_cbranch_execz .LBB0_958
	global_load_dwordx4 v[98:101], v[112:113], off offset:512 nt
	global_load_dwordx4 v[102:105], v[112:113], off offset:528 nt

.LBB0_967:
	s_or_b64 exec, exec, s[8:9]
	v_cmp_ne_u64_e32 vcc, 0, v[84:85]
	v_mov_b32_e32 v82, 0
	v_lshl_add_u64 v[96:97], v[160:161], 2, v[84:85]
	v_mov_b32_e32 v88, 0
	v_mov_b32_e32 v89, 0
	v_mov_b32_e32 v90, 0
	v_mov_b32_e32 v91, 0
	v_mov_b32_e32 v84, 0
	v_mov_b32_e32 v85, 0
	v_mov_b32_e32 v86, 0
	v_mov_b32_e32 v87, 0
	s_and_saveexec_b64 s[8:9], vcc
	s_cbranch_execz .LBB0_969
	global_load_dwordx4 v[88:91], v[96:97], off nt
	global_load_dwordx4 v[84:87], v[96:97], off offset:16 nt
.LBB0_969:
	s_or_b64 exec, exec, s[8:9]
	s_waitcnt lgkmcnt(0)
	v_add_u32_e32 v83, 0xffffbc30, v162
	v_cmp_gt_i32_e64 s[8:9], s87, v92
	v_mov_b32_e32 v100, s27
	v_lshlrev_b64 v[94:95], 11, v[92:93]
	v_cndmask_b32_e64 v98, v83, v92, s[8:9]
	v_mov_b32_e32 v83, s63
	v_cndmask_b32_e64 v99, 0, v93, s[8:9]
	v_cndmask_b32_e64 v101, v83, v100, s[8:9]
	v_mov_b32_e32 v83, s62
	v_mov_b32_e32 v100, s26
	v_cndmask_b32_e64 v100, v83, v100, s[8:9]
	v_lshlrev_b64 v[98:99], 12, v[98:99]
	v_lshl_add_u64 v[98:99], v[100:101], 0, v[98:99]
	s_waitcnt vmcnt(1)
	v_pk_fma_f32 v[80:81], v[80:81], 0.5, v[90:91] op_sel_hi:[1,0,1]
	v_pk_fma_f32 v[78:79], v[78:79], 0.5, v[88:89] op_sel_hi:[1,0,1]
	s_waitcnt vmcnt(0)
	v_pk_fma_f32 v[76:77], v[76:77], 0.5, v[86:87] op_sel_hi:[1,0,1]
	v_pk_fma_f32 v[74:75], v[74:75], 0.5, v[84:85] op_sel_hi:[1,0,1]
	v_lshl_add_u64 v[88:89], s[88:89], 0, v[94:95]
	v_lshl_add_u64 v[90:91], v[160:161], 2, v[98:99]
	v_cvt_pk_bf16_f32 v84, v78, v79
	v_cvt_pk_bf16_f32 v85, v80, v81
	v_cvt_pk_bf16_f32 v86, v74, v75
	v_cvt_pk_bf16_f32 v87, v76, v77
	v_lshl_add_u64 v[94:95], v[160:161], 1, v[88:89]
	global_store_dwordx4 v[90:91], v[78:81], off
	global_store_dwordx4 v[90:91], v[74:77], off offset:16
	global_store_dwordx4 v[94:95], v[84:87], off
	v_mov_b32_e32 v83, 0
	v_mov_b32_e32 v88, 0
	v_mov_b32_e32 v84, 0
	v_mov_b32_e32 v85, 0
	v_mov_b32_e32 v86, 0
	v_mov_b32_e32 v87, 0
	v_mov_b32_e32 v89, 0
	s_and_saveexec_b64 s[8:9], vcc
	s_cbranch_execz .LBB0_971
	global_load_dwordx4 v[82:85], v[96:97], off offset:512 nt
	global_load_dwordx4 v[86:89], v[96:97], off offset:528 nt

.LBB0_980:
	s_or_b64 exec, exec, s[8:9]
	v_cmp_ne_u64_e32 vcc, 0, v[68:69]
	v_mov_b32_e32 v66, 0
	v_lshl_add_u64 v[80:81], v[160:161], 2, v[68:69]
	v_mov_b32_e32 v72, 0
	v_mov_b32_e32 v73, 0
	v_mov_b32_e32 v74, 0
	v_mov_b32_e32 v75, 0
	v_mov_b32_e32 v68, 0
	v_mov_b32_e32 v69, 0
	v_mov_b32_e32 v70, 0
	v_mov_b32_e32 v71, 0
	s_and_saveexec_b64 s[8:9], vcc
	s_cbranch_execz .LBB0_982
	global_load_dwordx4 v[72:75], v[80:81], off nt
	global_load_dwordx4 v[68:71], v[80:81], off offset:16 nt
.LBB0_982:
	s_or_b64 exec, exec, s[8:9]
	s_waitcnt lgkmcnt(0)
	v_add_u32_e32 v67, 0xffffbc00, v76
	v_cmp_gt_i32_e64 s[8:9], s87, v76
	v_mov_b32_e32 v84, s27
	v_lshlrev_b64 v[78:79], 11, v[76:77]
	v_cndmask_b32_e64 v82, v67, v76, s[8:9]
	v_mov_b32_e32 v67, s63
	v_cndmask_b32_e64 v83, 0, v77, s[8:9]
	v_cndmask_b32_e64 v85, v67, v84, s[8:9]
	v_mov_b32_e32 v67, s62
	v_mov_b32_e32 v84, s26
	v_cndmask_b32_e64 v84, v67, v84, s[8:9]
	v_lshlrev_b64 v[82:83], 12, v[82:83]
	v_lshl_add_u64 v[82:83], v[84:85], 0, v[82:83]
	s_waitcnt vmcnt(1)
	v_pk_fma_f32 v[64:65], v[64:65], 0.5, v[74:75] op_sel_hi:[1,0,1]
	v_pk_fma_f32 v[62:63], v[62:63], 0.5, v[72:73] op_sel_hi:[1,0,1]
	s_waitcnt vmcnt(0)
	v_pk_fma_f32 v[60:61], v[60:61], 0.5, v[70:71] op_sel_hi:[1,0,1]
	v_pk_fma_f32 v[58:59], v[58:59], 0.5, v[68:69] op_sel_hi:[1,0,1]
	v_lshl_add_u64 v[72:73], s[88:89], 0, v[78:79]
	v_lshl_add_u64 v[74:75], v[160:161], 2, v[82:83]
	v_cvt_pk_bf16_f32 v68, v62, v63
	v_cvt_pk_bf16_f32 v69, v64, v65
	v_cvt_pk_bf16_f32 v70, v58, v59
	v_cvt_pk_bf16_f32 v71, v60, v61
	v_lshl_add_u64 v[78:79], v[160:161], 1, v[72:73]
	global_store_dwordx4 v[74:75], v[62:65], off
	global_store_dwordx4 v[74:75], v[58:61], off offset:16
	global_store_dwordx4 v[78:79], v[68:71], off
	v_mov_b32_e32 v67, 0
	v_mov_b32_e32 v72, 0
	v_mov_b32_e32 v68, 0
	v_mov_b32_e32 v69, 0
	v_mov_b32_e32 v70, 0
	v_mov_b32_e32 v71, 0
	v_mov_b32_e32 v73, 0
	s_and_saveexec_b64 s[8:9], vcc
	s_cbranch_execz .LBB0_984
	global_load_dwordx4 v[66:69], v[80:81], off offset:512 nt
	global_load_dwordx4 v[70:73], v[80:81], off offset:528 nt

.LBB0_993:
	s_or_b64 exec, exec, s[8:9]
	v_cmp_ne_u64_e32 vcc, 0, v[52:53]
	v_mov_b32_e32 v50, 0
	v_lshl_add_u64 v[64:65], v[160:161], 2, v[52:53]
	v_mov_b32_e32 v56, 0
	v_mov_b32_e32 v57, 0
	v_mov_b32_e32 v58, 0
	v_mov_b32_e32 v59, 0
	v_mov_b32_e32 v52, 0
	v_mov_b32_e32 v53, 0
	v_mov_b32_e32 v54, 0
	v_mov_b32_e32 v55, 0
	s_and_saveexec_b64 s[8:9], vcc
	s_cbranch_execz .LBB0_995
	global_load_dwordx4 v[56:59], v[64:65], off nt
	global_load_dwordx4 v[52:55], v[64:65], off offset:16 nt
.LBB0_995:
	s_or_b64 exec, exec, s[8:9]
	s_waitcnt lgkmcnt(0)
	v_add_u32_e32 v51, 0xffffbc00, v60
	v_cmp_gt_i32_e64 s[8:9], s87, v60
	v_mov_b32_e32 v68, s27
	v_lshlrev_b64 v[62:63], 11, v[60:61]
	v_cndmask_b32_e64 v66, v51, v60, s[8:9]
	v_mov_b32_e32 v51, s63
	v_cndmask_b32_e64 v67, 0, v61, s[8:9]
	v_cndmask_b32_e64 v69, v51, v68, s[8:9]
	v_mov_b32_e32 v51, s62
	v_mov_b32_e32 v68, s26
	v_cndmask_b32_e64 v68, v51, v68, s[8:9]
	v_lshlrev_b64 v[66:67], 12, v[66:67]
	v_lshl_add_u64 v[66:67], v[68:69], 0, v[66:67]
	s_waitcnt vmcnt(1)
	v_pk_fma_f32 v[48:49], v[48:49], 0.5, v[58:59] op_sel_hi:[1,0,1]
	v_pk_fma_f32 v[46:47], v[46:47], 0.5, v[56:57] op_sel_hi:[1,0,1]
	s_waitcnt vmcnt(0)
	v_pk_fma_f32 v[44:45], v[44:45], 0.5, v[54:55] op_sel_hi:[1,0,1]
	v_pk_fma_f32 v[42:43], v[42:43], 0.5, v[52:53] op_sel_hi:[1,0,1]
	v_lshl_add_u64 v[56:57], s[88:89], 0, v[62:63]
	v_lshl_add_u64 v[58:59], v[160:161], 2, v[66:67]
	v_cvt_pk_bf16_f32 v52, v46, v47
	v_cvt_pk_bf16_f32 v53, v48, v49
	v_cvt_pk_bf16_f32 v54, v42, v43
	v_cvt_pk_bf16_f32 v55, v44, v45
	v_lshl_add_u64 v[62:63], v[160:161], 1, v[56:57]
	global_store_dwordx4 v[58:59], v[46:49], off
	global_store_dwordx4 v[58:59], v[42:45], off offset:16
	global_store_dwordx4 v[62:63], v[52:55], off
	v_mov_b32_e32 v51, 0
	v_mov_b32_e32 v56, 0
	v_mov_b32_e32 v52, 0
	v_mov_b32_e32 v53, 0
	v_mov_b32_e32 v54, 0
	v_mov_b32_e32 v55, 0
	v_mov_b32_e32 v57, 0
	s_and_saveexec_b64 s[8:9], vcc
	s_cbranch_execz .LBB0_997
	global_load_dwordx4 v[50:53], v[64:65], off offset:512 nt
	global_load_dwordx4 v[54:57], v[64:65], off offset:528 nt

.LBB0_1006:
	s_or_b64 exec, exec, s[8:9]
	v_cmp_ne_u64_e32 vcc, 0, v[36:37]
	v_mov_b32_e32 v34, 0
	v_lshl_add_u64 v[48:49], v[160:161], 2, v[36:37]
	v_mov_b32_e32 v40, 0
	v_mov_b32_e32 v41, 0
	v_mov_b32_e32 v42, 0
	v_mov_b32_e32 v43, 0
	v_mov_b32_e32 v36, 0
	v_mov_b32_e32 v37, 0
	v_mov_b32_e32 v38, 0
	v_mov_b32_e32 v39, 0
	s_and_saveexec_b64 s[8:9], vcc
	s_cbranch_execz .LBB0_1008
	global_load_dwordx4 v[40:43], v[48:49], off nt
	global_load_dwordx4 v[36:39], v[48:49], off offset:16 nt
.LBB0_1008:
	s_or_b64 exec, exec, s[8:9]
	s_waitcnt lgkmcnt(0)
	v_add_u32_e32 v35, 0xffffbc00, v44
	v_cmp_gt_i32_e64 s[8:9], s87, v44
	v_mov_b32_e32 v52, s27
	v_lshlrev_b64 v[46:47], 11, v[44:45]
	v_cndmask_b32_e64 v50, v35, v44, s[8:9]
	v_mov_b32_e32 v35, s63
	v_cndmask_b32_e64 v51, 0, v45, s[8:9]
	v_cndmask_b32_e64 v53, v35, v52, s[8:9]
	v_mov_b32_e32 v35, s62
	v_mov_b32_e32 v52, s26
	v_cndmask_b32_e64 v52, v35, v52, s[8:9]
	v_lshlrev_b64 v[50:51], 12, v[50:51]
	v_lshl_add_u64 v[50:51], v[52:53], 0, v[50:51]
	s_waitcnt vmcnt(1)
	v_pk_fma_f32 v[32:33], v[32:33], 0.5, v[42:43] op_sel_hi:[1,0,1]
	v_pk_fma_f32 v[30:31], v[30:31], 0.5, v[40:41] op_sel_hi:[1,0,1]
	s_waitcnt vmcnt(0)
	v_pk_fma_f32 v[28:29], v[28:29], 0.5, v[38:39] op_sel_hi:[1,0,1]
	v_pk_fma_f32 v[26:27], v[26:27], 0.5, v[36:37] op_sel_hi:[1,0,1]
	v_lshl_add_u64 v[40:41], s[88:89], 0, v[46:47]
	v_lshl_add_u64 v[42:43], v[160:161], 2, v[50:51]
	v_cvt_pk_bf16_f32 v36, v30, v31
	v_cvt_pk_bf16_f32 v37, v32, v33
	v_cvt_pk_bf16_f32 v38, v26, v27
	v_cvt_pk_bf16_f32 v39, v28, v29
	v_lshl_add_u64 v[46:47], v[160:161], 1, v[40:41]
	global_store_dwordx4 v[42:43], v[30:33], off
	global_store_dwordx4 v[42:43], v[26:29], off offset:16
	global_store_dwordx4 v[46:47], v[36:39], off
	v_mov_b32_e32 v35, 0
	v_mov_b32_e32 v40, 0
	v_mov_b32_e32 v36, 0
	v_mov_b32_e32 v37, 0
	v_mov_b32_e32 v38, 0
	v_mov_b32_e32 v39, 0
	v_mov_b32_e32 v41, 0
	s_and_saveexec_b64 s[8:9], vcc
	s_cbranch_execz .LBB0_1010
	global_load_dwordx4 v[34:37], v[48:49], off offset:512 nt
	global_load_dwordx4 v[38:41], v[48:49], off offset:528 nt

.LBB0_1019:
	s_or_b64 exec, exec, s[8:9]
	v_cmp_ne_u64_e32 vcc, 0, v[20:21]
	v_mov_b32_e32 v18, 0
	v_lshl_add_u64 v[32:33], v[160:161], 2, v[20:21]
	v_mov_b32_e32 v24, 0
	v_mov_b32_e32 v25, 0
	v_mov_b32_e32 v26, 0
	v_mov_b32_e32 v27, 0
	v_mov_b32_e32 v20, 0
	v_mov_b32_e32 v21, 0
	v_mov_b32_e32 v22, 0
	v_mov_b32_e32 v23, 0
	s_and_saveexec_b64 s[8:9], vcc
	s_cbranch_execz .LBB0_1021
	global_load_dwordx4 v[24:27], v[32:33], off nt
	global_load_dwordx4 v[20:23], v[32:33], off offset:16 nt
.LBB0_1021:
	s_or_b64 exec, exec, s[8:9]
	s_waitcnt lgkmcnt(0)
	v_add_u32_e32 v19, 0xffffbc00, v28
	v_cmp_gt_i32_e64 s[8:9], s87, v28
	v_mov_b32_e32 v36, s27
	v_lshlrev_b64 v[30:31], 11, v[28:29]
	v_cndmask_b32_e64 v34, v19, v28, s[8:9]
	v_mov_b32_e32 v19, s63
	v_cndmask_b32_e64 v35, 0, v29, s[8:9]
	v_cndmask_b32_e64 v37, v19, v36, s[8:9]
	v_mov_b32_e32 v19, s62
	v_mov_b32_e32 v36, s26
	v_cndmask_b32_e64 v36, v19, v36, s[8:9]
	v_lshlrev_b64 v[34:35], 12, v[34:35]
	v_lshl_add_u64 v[34:35], v[36:37], 0, v[34:35]
	s_waitcnt vmcnt(1)
	v_pk_fma_f32 v[16:17], v[16:17], 0.5, v[26:27] op_sel_hi:[1,0,1]
	v_pk_fma_f32 v[14:15], v[14:15], 0.5, v[24:25] op_sel_hi:[1,0,1]
	s_waitcnt vmcnt(0)
	v_pk_fma_f32 v[12:13], v[12:13], 0.5, v[22:23] op_sel_hi:[1,0,1]
	v_pk_fma_f32 v[10:11], v[10:11], 0.5, v[20:21] op_sel_hi:[1,0,1]
	v_lshl_add_u64 v[24:25], s[88:89], 0, v[30:31]
	v_lshl_add_u64 v[26:27], v[160:161], 2, v[34:35]
	v_cvt_pk_bf16_f32 v20, v14, v15
	v_cvt_pk_bf16_f32 v21, v16, v17
	v_cvt_pk_bf16_f32 v22, v10, v11
	v_cvt_pk_bf16_f32 v23, v12, v13
	v_lshl_add_u64 v[30:31], v[160:161], 1, v[24:25]
	global_store_dwordx4 v[26:27], v[14:17], off
	global_store_dwordx4 v[26:27], v[10:13], off offset:16
	global_store_dwordx4 v[30:31], v[20:23], off
	v_mov_b32_e32 v19, 0
	v_mov_b32_e32 v24, 0
	v_mov_b32_e32 v20, 0
	v_mov_b32_e32 v21, 0
	v_mov_b32_e32 v22, 0
	v_mov_b32_e32 v23, 0
	v_mov_b32_e32 v25, 0
	s_and_saveexec_b64 s[8:9], vcc
	s_cbranch_execz .LBB0_1023
	global_load_dwordx4 v[18:21], v[32:33], off offset:512 nt
	global_load_dwordx4 v[22:25], v[32:33], off offset:528 nt
